# row-tile counter polls in the two fused epilogues also re-poll at once (no s_sleep), on top of the tight grid-barrier poll
# baseline (speedup 1.0000x reference)
.Lf7_poll:
	global_load_dword v155, v154, s[100:101] sc1
	s_waitcnt vmcnt(0)
	s_nop 0
	v_readfirstlane_b32 s28, v155
	s_add_i32 s29, s29, 1
	s_cmp_ge_u32 s28, 8
	s_cbranch_scc1 .Lf7_synced
	s_cmp_lt_u32 s29, 0x400000
	s_cbranch_scc1 .Lf7_poll

.Lfz_poll:
	global_load_dword v155, v154, s[100:101] sc1
	s_waitcnt vmcnt(0)
	s_nop 0
	v_readfirstlane_b32 s18, v155
	s_add_i32 s19, s19, 1
	s_cmp_ge_u32 s18, 8
	s_cbranch_scc1 .Lfz_synced
	s_cmp_lt_u32 s19, 0x400000
	s_cbranch_scc1 .Lfz_poll
